# DSA sparse-attention KV-loop body rewritten by hand: batched K/V fragment reads, scalar far/near test, bfe/bfi selection masking, folded far bias, packed sub/sum
# speedup vs baseline: 1.0372x; 1.0130x over previous
; #define LAS __attribute__((address_space(3)))
; __device__ __forceinline__ f32x16 mma32(const h16x8 a, const h16x8 b, const f32x16 c) { return __builtin_amdgcn_mfma_f32_32x32x16_f16(a, b, c, 0, 0, 0); }
; __device__ __forceinline__ void dsa_attn_item(CParams& p, LAS unsigned char* lds, int b, int qb, int tid_in, int wave) {
;     ...
;     for (int kt = 0; kt < nkt; ++kt) {
;         const int k0 = kt * 64; const int cur = kt & 1;
;         const LAS h16* Ks = Ks0 + cur * 8704; const LAS h16* Vt = Vt0 + cur * 9216;
;         const unsigned long long mk = mkn; mkn = bmq[kt + 1 < nkt ? kt + 1 : kt];
;         if (kt + 1 < nkt) ATT_STAGE(cur ^ 1, 2048, 2176, kt + 2);
;         if (__ballot(mk != 0ull) != 0ull) {
;             const bool far = (k0 + 63 + 128 <= q0);
;             const float bfar = bdh[128];
; #pragma unroll
;             for (int sub = 0; sub < 2; ++sub) {
;                 const unsigned mw = (unsigned)(mk >> (32 * sub));
;                 if (__ballot(mw != 0u) == 0ull) continue;
;                 f32x16 sc;
; #pragma unroll
;                 for (int i = 0; i < 16; ++i) sc[i] = 0.f;
; #pragma unroll
;                 for (int s = 0; s < 8; ++s) sc = mma32(*(const LAS h16x8*)(Ks + (32 * sub + r) * 136 + 16 * s + 8 * hh), qf[s], sc);
;                 float mx = -INFINITY;
; #pragma unroll
;                 for (int i = 0; i < 16; ++i) { const int ko = (i & 3) + 8 * (i >> 2) + 4 * hh; const int dist = qp - (k0 + 32 * sub + ko);
;                     float bias = bfar; if (!far) bias = bdh[dist < 0 ? 0 : (dist < 128 ? dist : 128)];
;                     const float v = ((mw >> ko) & 1u) ? sc[i] + bias : -INFINITY; sc[i] = v; mx = fmaxf(mx, v); }
.LBB0_514:
	s_waitcnt vmcnt(2)
	v_cmp_ne_u64_e32 vcc, 0, v[150:151]
	s_cbranch_vccz .LBB0_588
	s_and_b32 s4, s34, 1
	s_mul_i32 s5, s4, 0x4400
	s_mulk_i32 s4, 0x4800
	v_add3_u32 v197, v166, v169, s5
	v_add_u32_e32 v199, s4, v167
	v_lshl_add_u32 v227, v165, 1, v199
	v_add_u32_e32 v199, v199, v168
	v_readfirstlane_b32 s6, v145
	v_cmp_ne_u32_e32 vcc, 0, v150
	s_cbranch_vccz .LdsaA_s0_skip
	ds_read_b128 v[80:83], v197 offset:0
	ds_read_b128 v[84:87], v197 offset:32
	ds_read_b128 v[88:91], v197 offset:64
	ds_read_b128 v[92:95], v197 offset:96
	ds_read_b128 v[202:205], v197 offset:128
	ds_read_b128 v[206:209], v197 offset:160
	ds_read_b128 v[210:213], v197 offset:192
	ds_read_b128 v[228:231], v197 offset:224
	ds_read_b32 v200, v184 offset:512
	s_waitcnt lgkmcnt(5)
	v_mfma_f32_32x32x16_f16 v[236:251], v[80:83], v[112:115], 0
	v_mfma_f32_32x32x16_f16 v[236:251], v[84:87], v[2:5], v[236:251]
	v_mfma_f32_32x32x16_f16 v[236:251], v[88:91], v[6:9], v[236:251]
	v_mfma_f32_32x32x16_f16 v[236:251], v[92:95], v[10:13], v[236:251]
	s_waitcnt lgkmcnt(1)
	v_mfma_f32_32x32x16_f16 v[236:251], v[202:205], v[96:99], v[236:251]
	v_mfma_f32_32x32x16_f16 v[236:251], v[206:209], v[100:103], v[236:251]
	v_mfma_f32_32x32x16_f16 v[236:251], v[210:213], v[104:107], v[236:251]
	v_mfma_f32_32x32x16_f16 v[236:251], v[228:231], v[108:111], v[236:251]
	v_lshrrev_b32_e32 v214, v146, v150
	s_cmp_le_i32 s31, s6
	s_cbranch_scc1 .LdsaA_s0_far
	v_subrev_u32_e32 v202, 0, v196
	v_med3_i32 v202, v202, 0, v226
	v_lshl_add_u32 v202, v202, 2, v184
	ds_read_b32 v202, v202
	v_subrev_u32_e32 v203, 1, v196
	v_med3_i32 v203, v203, 0, v226
	v_lshl_add_u32 v203, v203, 2, v184
	ds_read_b32 v203, v203
	v_subrev_u32_e32 v204, 2, v196
	v_med3_i32 v204, v204, 0, v226
	v_lshl_add_u32 v204, v204, 2, v184
	ds_read_b32 v204, v204
	v_subrev_u32_e32 v205, 3, v196
	v_med3_i32 v205, v205, 0, v226
	v_lshl_add_u32 v205, v205, 2, v184
	ds_read_b32 v205, v205
	v_subrev_u32_e32 v206, 8, v196
	v_med3_i32 v206, v206, 0, v226
	v_lshl_add_u32 v206, v206, 2, v184
	ds_read_b32 v206, v206
	v_subrev_u32_e32 v207, 9, v196
	v_med3_i32 v207, v207, 0, v226
	v_lshl_add_u32 v207, v207, 2, v184
	ds_read_b32 v207, v207
	v_subrev_u32_e32 v208, 10, v196
	v_med3_i32 v208, v208, 0, v226
	v_lshl_add_u32 v208, v208, 2, v184
	ds_read_b32 v208, v208
	v_subrev_u32_e32 v209, 11, v196
	v_med3_i32 v209, v209, 0, v226
	v_lshl_add_u32 v209, v209, 2, v184
	ds_read_b32 v209, v209
	v_subrev_u32_e32 v210, 16, v196
	v_med3_i32 v210, v210, 0, v226
	v_lshl_add_u32 v210, v210, 2, v184
	ds_read_b32 v210, v210
	v_subrev_u32_e32 v211, 17, v196
	v_med3_i32 v211, v211, 0, v226
	v_lshl_add_u32 v211, v211, 2, v184
	ds_read_b32 v211, v211
	v_subrev_u32_e32 v212, 18, v196
	v_med3_i32 v212, v212, 0, v226
	v_lshl_add_u32 v212, v212, 2, v184
	ds_read_b32 v212, v212
	v_subrev_u32_e32 v213, 19, v196
	v_med3_i32 v213, v213, 0, v226
	v_lshl_add_u32 v213, v213, 2, v184
	ds_read_b32 v213, v213
	v_subrev_u32_e32 v80, 24, v196
	v_med3_i32 v80, v80, 0, v226
	v_lshl_add_u32 v80, v80, 2, v184
	ds_read_b32 v80, v80
	v_subrev_u32_e32 v81, 25, v196
	v_med3_i32 v81, v81, 0, v226
	v_lshl_add_u32 v81, v81, 2, v184
	ds_read_b32 v81, v81
	v_subrev_u32_e32 v82, 26, v196
	v_med3_i32 v82, v82, 0, v226
	v_lshl_add_u32 v82, v82, 2, v184
	ds_read_b32 v82, v82
	v_subrev_u32_e32 v83, 27, v196
	v_med3_i32 v83, v83, 0, v226
	v_lshl_add_u32 v83, v83, 2, v184
	ds_read_b32 v83, v83
	s_waitcnt lgkmcnt(0)
	s_nop 2
	v_add_f32_e32 v236, v236, v202
	v_add_f32_e32 v237, v237, v203
	v_add_f32_e32 v238, v238, v204
	v_add_f32_e32 v239, v239, v205
	v_add_f32_e32 v240, v240, v206
	v_add_f32_e32 v241, v241, v207
	v_add_f32_e32 v242, v242, v208
	v_add_f32_e32 v243, v243, v209
	v_add_f32_e32 v244, v244, v210
	v_add_f32_e32 v245, v245, v211
	v_add_f32_e32 v246, v246, v212
	v_add_f32_e32 v247, v247, v213
	v_add_f32_e32 v248, v248, v80
	v_add_f32_e32 v249, v249, v81
	v_add_f32_e32 v250, v250, v82
	v_add_f32_e32 v251, v251, v83
	v_mov_b32_e32 v200, 0
	s_branch .LdsaA_s0_msk
.LdsaA_s0_far:
	s_nop 7
	s_nop 2
.LdsaA_s0_msk:
	v_bfe_i32 v80, v214, 0, 1
	v_bfi_b32 v236, v80, v236, v225
	v_bfe_i32 v81, v214, 1, 1
	v_bfi_b32 v237, v81, v237, v225
	v_bfe_i32 v82, v214, 2, 1
	v_bfi_b32 v238, v82, v238, v225
	v_bfe_i32 v83, v214, 3, 1
	v_bfi_b32 v239, v83, v239, v225
	v_bfe_i32 v80, v214, 8, 1
	v_bfi_b32 v240, v80, v240, v225
	v_bfe_i32 v81, v214, 9, 1
	v_bfi_b32 v241, v81, v241, v225
	v_bfe_i32 v82, v214, 10, 1
	v_bfi_b32 v242, v82, v242, v225
	v_bfe_i32 v83, v214, 11, 1
	v_bfi_b32 v243, v83, v243, v225
	v_bfe_i32 v80, v214, 16, 1
	v_bfi_b32 v244, v80, v244, v225
	v_bfe_i32 v81, v214, 17, 1
	v_bfi_b32 v245, v81, v245, v225
	v_bfe_i32 v82, v214, 18, 1
	v_bfi_b32 v246, v82, v246, v225
	v_bfe_i32 v83, v214, 19, 1
	v_bfi_b32 v247, v83, v247, v225
	v_bfe_i32 v80, v214, 24, 1
	v_bfi_b32 v248, v80, v248, v225
	v_bfe_i32 v81, v214, 25, 1
	v_bfi_b32 v249, v81, v249, v225
	v_bfe_i32 v82, v214, 26, 1
	v_bfi_b32 v250, v82, v250, v225
	v_bfe_i32 v83, v214, 27, 1
	v_bfi_b32 v251, v83, v251, v225
	v_max3_f32 v84, v236, v237, v238
	v_max3_f32 v84, v84, v239, v240
	v_max3_f32 v84, v84, v241, v242
	v_max3_f32 v84, v84, v243, v244
	v_max3_f32 v84, v84, v245, v246
	v_max3_f32 v84, v84, v247, v248
	v_max3_f32 v84, v84, v249, v250
	v_max_f32_e32 v84, v84, v251
	s_waitcnt lgkmcnt(0)
	v_add_f32_e32 v84, v84, v200
	ds_bpermute_b32 v215, v185, v84
	s_waitcnt lgkmcnt(0)
; __device__ __forceinline__ void dsa_attn_item(CParams& p, LAS unsigned char* lds, int b, int qb, int tid_in, int wave) {
;     ...
;                 mx = fmaxf(mx, __shfl_xor(mx, 32));
;                 const float m_new = fmaxf(m_run, mx);
;                 const float msafe = (m_new == -INFINITY) ? 0.f : m_new;
;                 const float alpha = __builtin_amdgcn_exp2f(m_run - msafe);
;                 const bool resc = __ballot(m_new > m_run) != 0ull;
;                 float ls = 0.f;
; #pragma unroll
;                 for (int i = 0; i < 16; ++i) { const float e = __builtin_amdgcn_exp2f(sc[i] - msafe); sc[i] = e; ls += e; }
;                 ls += __shfl_xor(ls, 32);
;                 l_run = l_run * alpha + ls; m_run = m_new;
;                 if (resc) {
; #pragma unroll
;                     for (int d = 0; d < 4; ++d)
; #pragma unroll
;                         for (int i = 0; i < 16; ++i) o[d][i] *= alpha;
;                 }
	v_max3_f32 v85, v201, v84, v215
	v_cmp_neq_f32_e32 vcc, s78, v85
	s_nop 1
	v_cndmask_b32_e32 v86, 0, v85, vcc
	v_sub_f32_e32 v88, v201, v86
	v_exp_f32_e32 v88, v88
	v_cmp_gt_f32_e32 vcc, v85, v201
	v_sub_f32_e32 v90, v86, v200
	v_mov_b32_e32 v201, v85
	v_pk_add_f32 v[236:237], v[236:237], v[90:91] op_sel_hi:[1,0] neg_lo:[0,1] neg_hi:[0,1]
	v_pk_add_f32 v[238:239], v[238:239], v[90:91] op_sel_hi:[1,0] neg_lo:[0,1] neg_hi:[0,1]
	v_pk_add_f32 v[240:241], v[240:241], v[90:91] op_sel_hi:[1,0] neg_lo:[0,1] neg_hi:[0,1]
	v_pk_add_f32 v[242:243], v[242:243], v[90:91] op_sel_hi:[1,0] neg_lo:[0,1] neg_hi:[0,1]
	v_pk_add_f32 v[244:245], v[244:245], v[90:91] op_sel_hi:[1,0] neg_lo:[0,1] neg_hi:[0,1]
	v_pk_add_f32 v[246:247], v[246:247], v[90:91] op_sel_hi:[1,0] neg_lo:[0,1] neg_hi:[0,1]
	v_pk_add_f32 v[248:249], v[248:249], v[90:91] op_sel_hi:[1,0] neg_lo:[0,1] neg_hi:[0,1]
	v_pk_add_f32 v[250:251], v[250:251], v[90:91] op_sel_hi:[1,0] neg_lo:[0,1] neg_hi:[0,1]
	v_exp_f32_e32 v236, v236
	v_exp_f32_e32 v237, v237
	v_exp_f32_e32 v238, v238
	v_exp_f32_e32 v239, v239
	v_exp_f32_e32 v240, v240
	v_exp_f32_e32 v241, v241
	v_exp_f32_e32 v242, v242
	v_exp_f32_e32 v243, v243
	v_exp_f32_e32 v244, v244
	v_exp_f32_e32 v245, v245
	v_exp_f32_e32 v246, v246
	v_exp_f32_e32 v247, v247
	v_exp_f32_e32 v248, v248
	v_exp_f32_e32 v249, v249
	v_exp_f32_e32 v250, v250
	v_exp_f32_e32 v251, v251
	v_pk_add_f32 v[92:93], v[236:237], v[238:239]
	v_pk_add_f32 v[92:93], v[92:93], v[240:241]
	v_pk_add_f32 v[92:93], v[92:93], v[242:243]
	v_pk_add_f32 v[92:93], v[92:93], v[244:245]
	v_pk_add_f32 v[92:93], v[92:93], v[246:247]
	v_pk_add_f32 v[92:93], v[92:93], v[248:249]
	v_pk_add_f32 v[92:93], v[92:93], v[250:251]
	s_nop 0
	v_add_f32_e32 v92, v92, v93
	ds_bpermute_b32 v215, v185, v92
	v_cvt_pk_f16_f32 v232, v236, v237
	v_cvt_pk_f16_f32 v233, v238, v239
	v_cvt_pk_f16_f32 v234, v240, v241
	v_cvt_pk_f16_f32 v235, v242, v243
	v_cvt_pk_f16_f32 v228, v244, v245
	v_cvt_pk_f16_f32 v229, v246, v247
	v_cvt_pk_f16_f32 v230, v248, v249
	v_cvt_pk_f16_f32 v231, v250, v251
	s_waitcnt lgkmcnt(0)
	v_add_f32_e32 v92, v92, v215
	v_fma_f32 v198, v198, v88, v92
	ds_read_b64 v[236:237], v199 offset:34848
	ds_read_b64 v[238:239], v227 offset:34848
	ds_read_b64 v[240:241], v199 offset:39424
	ds_read_b64 v[242:243], v227 offset:39424
	ds_read_b64 v[244:245], v199 offset:44128
	ds_read_b64 v[246:247], v227 offset:44128
	ds_read_b64 v[248:249], v199 offset:48704
	ds_read_b64 v[250:251], v227 offset:48704
	s_cbranch_vccz .LdsaA_s0_noresc
	v_pk_mul_f32 v[64:65], v[64:65], v[88:89] op_sel_hi:[1,0]
	v_pk_mul_f32 v[66:67], v[66:67], v[88:89] op_sel_hi:[1,0]
	v_pk_mul_f32 v[68:69], v[68:69], v[88:89] op_sel_hi:[1,0]
	v_pk_mul_f32 v[70:71], v[70:71], v[88:89] op_sel_hi:[1,0]
	v_pk_mul_f32 v[72:73], v[72:73], v[88:89] op_sel_hi:[1,0]
	v_pk_mul_f32 v[74:75], v[74:75], v[88:89] op_sel_hi:[1,0]
	v_pk_mul_f32 v[76:77], v[76:77], v[88:89] op_sel_hi:[1,0]
	v_pk_mul_f32 v[78:79], v[78:79], v[88:89] op_sel_hi:[1,0]
	v_pk_mul_f32 v[48:49], v[48:49], v[88:89] op_sel_hi:[1,0]
	v_pk_mul_f32 v[50:51], v[50:51], v[88:89] op_sel_hi:[1,0]
	v_pk_mul_f32 v[52:53], v[52:53], v[88:89] op_sel_hi:[1,0]
	v_pk_mul_f32 v[54:55], v[54:55], v[88:89] op_sel_hi:[1,0]
	v_pk_mul_f32 v[56:57], v[56:57], v[88:89] op_sel_hi:[1,0]
	v_pk_mul_f32 v[58:59], v[58:59], v[88:89] op_sel_hi:[1,0]
	v_pk_mul_f32 v[60:61], v[60:61], v[88:89] op_sel_hi:[1,0]
	v_pk_mul_f32 v[62:63], v[62:63], v[88:89] op_sel_hi:[1,0]
	v_pk_mul_f32 v[32:33], v[32:33], v[88:89] op_sel_hi:[1,0]
	v_pk_mul_f32 v[34:35], v[34:35], v[88:89] op_sel_hi:[1,0]
	v_pk_mul_f32 v[36:37], v[36:37], v[88:89] op_sel_hi:[1,0]
	v_pk_mul_f32 v[38:39], v[38:39], v[88:89] op_sel_hi:[1,0]
	v_pk_mul_f32 v[40:41], v[40:41], v[88:89] op_sel_hi:[1,0]
	v_pk_mul_f32 v[42:43], v[42:43], v[88:89] op_sel_hi:[1,0]
	v_pk_mul_f32 v[44:45], v[44:45], v[88:89] op_sel_hi:[1,0]
	v_pk_mul_f32 v[46:47], v[46:47], v[88:89] op_sel_hi:[1,0]
	v_pk_mul_f32 v[16:17], v[16:17], v[88:89] op_sel_hi:[1,0]
	v_pk_mul_f32 v[18:19], v[18:19], v[88:89] op_sel_hi:[1,0]
	v_pk_mul_f32 v[20:21], v[20:21], v[88:89] op_sel_hi:[1,0]
	v_pk_mul_f32 v[22:23], v[22:23], v[88:89] op_sel_hi:[1,0]
	v_pk_mul_f32 v[24:25], v[24:25], v[88:89] op_sel_hi:[1,0]
	v_pk_mul_f32 v[26:27], v[26:27], v[88:89] op_sel_hi:[1,0]
	v_pk_mul_f32 v[28:29], v[28:29], v[88:89] op_sel_hi:[1,0]
	v_pk_mul_f32 v[30:31], v[30:31], v[88:89] op_sel_hi:[1,0]
; #define LAS __attribute__((address_space(3)))
; __device__ __forceinline__ f32x16 mma32(const h16x8 a, const h16x8 b, const f32x16 c) { return __builtin_amdgcn_mfma_f32_32x32x16_f16(a, b, c, 0, 0, 0); }
; __device__ __forceinline__ void dsa_attn_item(CParams& p, LAS unsigned char* lds, int b, int qb, int tid_in, int wave) {
;     ...
;             for (int sub = 0; sub < 2; ++sub) {
;                 const unsigned mw = (unsigned)(mk >> (32 * sub));
;                 if (__ballot(mw != 0u) == 0ull) continue;
;                 f32x16 sc;
; #pragma unroll
;                 for (int i = 0; i < 16; ++i) sc[i] = 0.f;
; #pragma unroll
;                 for (int s = 0; s < 8; ++s) sc = mma32(*(const LAS h16x8*)(Ks + (32 * sub + r) * 136 + 16 * s + 8 * hh), qf[s], sc);
;                 float mx = -INFINITY;
; #pragma unroll
;                 for (int i = 0; i < 16; ++i) { const int ko = (i & 3) + 8 * (i >> 2) + 4 * hh; const int dist = qp - (k0 + 32 * sub + ko);
;                     float bias = bfar; if (!far) bias = bdh[dist < 0 ? 0 : (dist < 128 ? dist : 128)];
;                     const float v = ((mw >> ko) & 1u) ? sc[i] + bias : -INFINITY; sc[i] = v; mx = fmaxf(mx, v); }
;     ...
; #pragma unroll
;                 for (int s2 = 0; s2 < 2; ++s2) {
;                     h16x8 pf;
; #pragma unroll
;                     for (int jj = 0; jj < 8; ++jj) pf[jj] = (h16)sc[8 * s2 + jj];
; #pragma unroll
;                     for (int d = 0; d < 4; ++d) {
;                         const int coff = 32 * d * 72 + ((((sub << 1) | s2) ^ d) << 4);
;                         const h16x4 lo = *(const LAS h16x4*)(Vt + vlo + coff), hi = *(const LAS h16x4*)(Vt + vhi + coff);
;                         h16x8 vf; vf[0] = lo[0]; vf[1] = lo[1]; vf[2] = lo[2]; vf[3] = lo[3]; vf[4] = hi[0]; vf[5] = hi[1]; vf[6] = hi[2]; vf[7] = hi[3];
;                         o[d] = mma32(vf, pf, o[d]);
;                     }
;                 }
.LdsaA_s0_noresc:
	ds_read_b64 v[80:81], v199 offset:34816
	ds_read_b64 v[82:83], v227 offset:34816
	ds_read_b64 v[84:85], v199 offset:39456
	ds_read_b64 v[86:87], v227 offset:39456
	ds_read_b64 v[88:89], v199 offset:44096
	ds_read_b64 v[90:91], v227 offset:44096
	ds_read_b64 v[92:93], v199 offset:48736
	ds_read_b64 v[94:95], v227 offset:48736
	s_waitcnt lgkmcnt(8)
	v_mfma_f32_32x32x16_f16 v[64:79], v[236:239], v[228:231], v[64:79]
	v_mfma_f32_32x32x16_f16 v[48:63], v[240:243], v[228:231], v[48:63]
	v_mfma_f32_32x32x16_f16 v[32:47], v[244:247], v[228:231], v[32:47]
	v_mfma_f32_32x32x16_f16 v[16:31], v[248:251], v[228:231], v[16:31]
	s_waitcnt lgkmcnt(0)
	v_mfma_f32_32x32x16_f16 v[64:79], v[80:83], v[232:235], v[64:79]
	v_mfma_f32_32x32x16_f16 v[48:63], v[84:87], v[232:235], v[48:63]
	v_mfma_f32_32x32x16_f16 v[32:47], v[88:91], v[232:235], v[32:47]
	v_mfma_f32_32x32x16_f16 v[16:31], v[92:95], v[232:235], v[16:31]
.LdsaA_s0_skip:
	v_cmp_ne_u32_e32 vcc, 0, v151
	s_cbranch_vccz .LdsaA_s1_skip
	ds_read_b128 v[80:83], v197 offset:8704
	ds_read_b128 v[84:87], v197 offset:8736
	ds_read_b128 v[88:91], v197 offset:8768
	ds_read_b128 v[92:95], v197 offset:8800
	ds_read_b128 v[202:205], v197 offset:8832
	ds_read_b128 v[206:209], v197 offset:8864
	ds_read_b128 v[210:213], v197 offset:8896
	ds_read_b128 v[228:231], v197 offset:8928
	ds_read_b32 v200, v184 offset:512
	s_waitcnt lgkmcnt(5)
	v_mfma_f32_32x32x16_f16 v[236:251], v[80:83], v[112:115], 0
	v_mfma_f32_32x32x16_f16 v[236:251], v[84:87], v[2:5], v[236:251]
	v_mfma_f32_32x32x16_f16 v[236:251], v[88:91], v[6:9], v[236:251]
	v_mfma_f32_32x32x16_f16 v[236:251], v[92:95], v[10:13], v[236:251]
	s_waitcnt lgkmcnt(1)
	v_mfma_f32_32x32x16_f16 v[236:251], v[202:205], v[96:99], v[236:251]
	v_mfma_f32_32x32x16_f16 v[236:251], v[206:209], v[100:103], v[236:251]
	v_mfma_f32_32x32x16_f16 v[236:251], v[210:213], v[104:107], v[236:251]
	v_mfma_f32_32x32x16_f16 v[236:251], v[228:231], v[108:111], v[236:251]
	v_lshrrev_b32_e32 v214, v146, v151
	s_cmp_le_i32 s31, s6
	s_cbranch_scc1 .LdsaA_s1_far
	v_subrev_u32_e32 v202, 32, v196
	v_med3_i32 v202, v202, 0, v226
	v_lshl_add_u32 v202, v202, 2, v184
	ds_read_b32 v202, v202
	v_subrev_u32_e32 v203, 33, v196
	v_med3_i32 v203, v203, 0, v226
	v_lshl_add_u32 v203, v203, 2, v184
	ds_read_b32 v203, v203
	v_subrev_u32_e32 v204, 34, v196
	v_med3_i32 v204, v204, 0, v226
	v_lshl_add_u32 v204, v204, 2, v184
	ds_read_b32 v204, v204
	v_subrev_u32_e32 v205, 35, v196
	v_med3_i32 v205, v205, 0, v226
	v_lshl_add_u32 v205, v205, 2, v184
	ds_read_b32 v205, v205
	v_subrev_u32_e32 v206, 40, v196
	v_med3_i32 v206, v206, 0, v226
	v_lshl_add_u32 v206, v206, 2, v184
	ds_read_b32 v206, v206
	v_subrev_u32_e32 v207, 41, v196
	v_med3_i32 v207, v207, 0, v226
	v_lshl_add_u32 v207, v207, 2, v184
	ds_read_b32 v207, v207
	v_subrev_u32_e32 v208, 42, v196
	v_med3_i32 v208, v208, 0, v226
	v_lshl_add_u32 v208, v208, 2, v184
	ds_read_b32 v208, v208
	v_subrev_u32_e32 v209, 43, v196
	v_med3_i32 v209, v209, 0, v226
	v_lshl_add_u32 v209, v209, 2, v184
	ds_read_b32 v209, v209
	v_subrev_u32_e32 v210, 48, v196
	v_med3_i32 v210, v210, 0, v226
	v_lshl_add_u32 v210, v210, 2, v184
	ds_read_b32 v210, v210
	v_subrev_u32_e32 v211, 49, v196
	v_med3_i32 v211, v211, 0, v226
	v_lshl_add_u32 v211, v211, 2, v184
	ds_read_b32 v211, v211
	v_subrev_u32_e32 v212, 50, v196
	v_med3_i32 v212, v212, 0, v226
	v_lshl_add_u32 v212, v212, 2, v184
	ds_read_b32 v212, v212
	v_subrev_u32_e32 v213, 51, v196
	v_med3_i32 v213, v213, 0, v226
	v_lshl_add_u32 v213, v213, 2, v184
	ds_read_b32 v213, v213
	v_subrev_u32_e32 v80, 56, v196
	v_med3_i32 v80, v80, 0, v226
	v_lshl_add_u32 v80, v80, 2, v184
	ds_read_b32 v80, v80
	v_subrev_u32_e32 v81, 57, v196
	v_med3_i32 v81, v81, 0, v226
	v_lshl_add_u32 v81, v81, 2, v184
	ds_read_b32 v81, v81
	v_subrev_u32_e32 v82, 58, v196
	v_med3_i32 v82, v82, 0, v226
	v_lshl_add_u32 v82, v82, 2, v184
	ds_read_b32 v82, v82
	v_subrev_u32_e32 v83, 59, v196
	v_med3_i32 v83, v83, 0, v226
	v_lshl_add_u32 v83, v83, 2, v184
	ds_read_b32 v83, v83
	s_waitcnt lgkmcnt(0)
	s_nop 2
	v_add_f32_e32 v236, v236, v202
	v_add_f32_e32 v237, v237, v203
	v_add_f32_e32 v238, v238, v204
	v_add_f32_e32 v239, v239, v205
	v_add_f32_e32 v240, v240, v206
	v_add_f32_e32 v241, v241, v207
	v_add_f32_e32 v242, v242, v208
	v_add_f32_e32 v243, v243, v209
	v_add_f32_e32 v244, v244, v210
	v_add_f32_e32 v245, v245, v211
	v_add_f32_e32 v246, v246, v212
	v_add_f32_e32 v247, v247, v213
	v_add_f32_e32 v248, v248, v80
	v_add_f32_e32 v249, v249, v81
	v_add_f32_e32 v250, v250, v82
	v_add_f32_e32 v251, v251, v83
	v_mov_b32_e32 v200, 0
	s_branch .LdsaA_s1_msk

; #define LAS __attribute__((address_space(3)))
; __device__ __forceinline__ f32x16 mma32(const h16x8 a, const h16x8 b, const f32x16 c) { return __builtin_amdgcn_mfma_f32_32x32x16_f16(a, b, c, 0, 0, 0); }
; __device__ __forceinline__ void dsa_attn_item(CParams& p, LAS unsigned char* lds, int b, int qb, int tid_in, int wave) {
;     ...
;                 for (int i = 0; i < 16; ++i) { const int ko = (i & 3) + 8 * (i >> 2) + 4 * hh; const int dist = qp - (k0 + 32 * sub + ko);
;                     float bias = bfar; if (!far) bias = bdh[dist < 0 ? 0 : (dist < 128 ? dist : 128)];
;                     const float v = ((mw >> ko) & 1u) ? sc[i] + bias : -INFINITY; sc[i] = v; mx = fmaxf(mx, v); }
;                 mx = fmaxf(mx, __shfl_xor(mx, 32));
;                 const float m_new = fmaxf(m_run, mx);
;                 const float msafe = (m_new == -INFINITY) ? 0.f : m_new;
;                 const float alpha = __builtin_amdgcn_exp2f(m_run - msafe);
;                 const bool resc = __ballot(m_new > m_run) != 0ull;
;                 float ls = 0.f;
; #pragma unroll
;                 for (int i = 0; i < 16; ++i) { const float e = __builtin_amdgcn_exp2f(sc[i] - msafe); sc[i] = e; ls += e; }
;                 ls += __shfl_xor(ls, 32);
;                 l_run = l_run * alpha + ls; m_run = m_new;
;                 if (resc) {
; #pragma unroll
;                     for (int d = 0; d < 4; ++d)
; #pragma unroll
;                         for (int i = 0; i < 16; ++i) o[d][i] *= alpha;
;                 }
; #pragma unroll
;                 for (int s2 = 0; s2 < 2; ++s2) {
;                     h16x8 pf;
; #pragma unroll
;                     for (int jj = 0; jj < 8; ++jj) pf[jj] = (h16)sc[8 * s2 + jj];
; #pragma unroll
;                     for (int d = 0; d < 4; ++d) {
;                         const int coff = 32 * d * 72 + ((((sub << 1) | s2) ^ d) << 4);
;                         const h16x4 lo = *(const LAS h16x4*)(Vt + vlo + coff), hi = *(const LAS h16x4*)(Vt + vhi + coff);
;                         h16x8 vf; vf[0] = lo[0]; vf[1] = lo[1]; vf[2] = lo[2]; vf[3] = lo[3]; vf[4] = hi[0]; vf[5] = hi[1]; vf[6] = hi[2]; vf[7] = hi[3];
;                         o[d] = mma32(vf, pf, o[d]);
;                     }
;                 }
;             }
;         }
;         __syncthreads();
.LdsaA_s1_msk:
	v_bfe_i32 v80, v214, 0, 1
	v_bfi_b32 v236, v80, v236, v225
	v_bfe_i32 v81, v214, 1, 1
	v_bfi_b32 v237, v81, v237, v225
	v_bfe_i32 v82, v214, 2, 1
	v_bfi_b32 v238, v82, v238, v225
	v_bfe_i32 v83, v214, 3, 1
	v_bfi_b32 v239, v83, v239, v225
	v_bfe_i32 v80, v214, 8, 1
	v_bfi_b32 v240, v80, v240, v225
	v_bfe_i32 v81, v214, 9, 1
	v_bfi_b32 v241, v81, v241, v225
	v_bfe_i32 v82, v214, 10, 1
	v_bfi_b32 v242, v82, v242, v225
	v_bfe_i32 v83, v214, 11, 1
	v_bfi_b32 v243, v83, v243, v225
	v_bfe_i32 v80, v214, 16, 1
	v_bfi_b32 v244, v80, v244, v225
	v_bfe_i32 v81, v214, 17, 1
	v_bfi_b32 v245, v81, v245, v225
	v_bfe_i32 v82, v214, 18, 1
	v_bfi_b32 v246, v82, v246, v225
	v_bfe_i32 v83, v214, 19, 1
	v_bfi_b32 v247, v83, v247, v225
	v_bfe_i32 v80, v214, 24, 1
	v_bfi_b32 v248, v80, v248, v225
	v_bfe_i32 v81, v214, 25, 1
	v_bfi_b32 v249, v81, v249, v225
	v_bfe_i32 v82, v214, 26, 1
	v_bfi_b32 v250, v82, v250, v225
	v_bfe_i32 v83, v214, 27, 1
	v_bfi_b32 v251, v83, v251, v225
	v_max3_f32 v84, v236, v237, v238
	v_max3_f32 v84, v84, v239, v240
	v_max3_f32 v84, v84, v241, v242
	v_max3_f32 v84, v84, v243, v244
	v_max3_f32 v84, v84, v245, v246
	v_max3_f32 v84, v84, v247, v248
	v_max3_f32 v84, v84, v249, v250
	v_max_f32_e32 v84, v84, v251
	s_waitcnt lgkmcnt(0)
	v_add_f32_e32 v84, v84, v200
	ds_bpermute_b32 v215, v185, v84
	s_waitcnt lgkmcnt(0)
	v_max3_f32 v85, v201, v84, v215
	v_cmp_neq_f32_e32 vcc, s78, v85
	s_nop 1
	v_cndmask_b32_e32 v86, 0, v85, vcc
	v_sub_f32_e32 v88, v201, v86
	v_exp_f32_e32 v88, v88
	v_cmp_gt_f32_e32 vcc, v85, v201
	v_sub_f32_e32 v90, v86, v200
	v_mov_b32_e32 v201, v85
	v_pk_add_f32 v[236:237], v[236:237], v[90:91] op_sel_hi:[1,0] neg_lo:[0,1] neg_hi:[0,1]
	v_pk_add_f32 v[238:239], v[238:239], v[90:91] op_sel_hi:[1,0] neg_lo:[0,1] neg_hi:[0,1]
	v_pk_add_f32 v[240:241], v[240:241], v[90:91] op_sel_hi:[1,0] neg_lo:[0,1] neg_hi:[0,1]
	v_pk_add_f32 v[242:243], v[242:243], v[90:91] op_sel_hi:[1,0] neg_lo:[0,1] neg_hi:[0,1]
	v_pk_add_f32 v[244:245], v[244:245], v[90:91] op_sel_hi:[1,0] neg_lo:[0,1] neg_hi:[0,1]
	v_pk_add_f32 v[246:247], v[246:247], v[90:91] op_sel_hi:[1,0] neg_lo:[0,1] neg_hi:[0,1]
	v_pk_add_f32 v[248:249], v[248:249], v[90:91] op_sel_hi:[1,0] neg_lo:[0,1] neg_hi:[0,1]
	v_pk_add_f32 v[250:251], v[250:251], v[90:91] op_sel_hi:[1,0] neg_lo:[0,1] neg_hi:[0,1]
	v_exp_f32_e32 v236, v236
	v_exp_f32_e32 v237, v237
	v_exp_f32_e32 v238, v238
	v_exp_f32_e32 v239, v239
	v_exp_f32_e32 v240, v240
	v_exp_f32_e32 v241, v241
	v_exp_f32_e32 v242, v242
	v_exp_f32_e32 v243, v243
	v_exp_f32_e32 v244, v244
	v_exp_f32_e32 v245, v245
	v_exp_f32_e32 v246, v246
	v_exp_f32_e32 v247, v247
	v_exp_f32_e32 v248, v248
	v_exp_f32_e32 v249, v249
	v_exp_f32_e32 v250, v250
	v_exp_f32_e32 v251, v251
	v_pk_add_f32 v[92:93], v[236:237], v[238:239]
	v_pk_add_f32 v[92:93], v[92:93], v[240:241]
	v_pk_add_f32 v[92:93], v[92:93], v[242:243]
	v_pk_add_f32 v[92:93], v[92:93], v[244:245]
	v_pk_add_f32 v[92:93], v[92:93], v[246:247]
	v_pk_add_f32 v[92:93], v[92:93], v[248:249]
	v_pk_add_f32 v[92:93], v[92:93], v[250:251]
	s_nop 0
	v_add_f32_e32 v92, v92, v93
	ds_bpermute_b32 v215, v185, v92
	v_cvt_pk_f16_f32 v232, v236, v237
	v_cvt_pk_f16_f32 v233, v238, v239
	v_cvt_pk_f16_f32 v234, v240, v241
	v_cvt_pk_f16_f32 v235, v242, v243
	v_cvt_pk_f16_f32 v228, v244, v245
	v_cvt_pk_f16_f32 v229, v246, v247
	v_cvt_pk_f16_f32 v230, v248, v249
	v_cvt_pk_f16_f32 v231, v250, v251
	s_waitcnt lgkmcnt(0)
	v_add_f32_e32 v92, v92, v215
	v_fma_f32 v198, v198, v88, v92
	ds_read_b64 v[236:237], v199 offset:34912
	ds_read_b64 v[238:239], v227 offset:34912
	ds_read_b64 v[240:241], v199 offset:39488
	ds_read_b64 v[242:243], v227 offset:39488
	ds_read_b64 v[244:245], v199 offset:44064
	ds_read_b64 v[246:247], v227 offset:44064
	ds_read_b64 v[248:249], v199 offset:48640
	ds_read_b64 v[250:251], v227 offset:48640
	s_cbranch_vccz .LdsaA_s1_noresc
	v_pk_mul_f32 v[64:65], v[64:65], v[88:89] op_sel_hi:[1,0]
	v_pk_mul_f32 v[66:67], v[66:67], v[88:89] op_sel_hi:[1,0]
	v_pk_mul_f32 v[68:69], v[68:69], v[88:89] op_sel_hi:[1,0]
	v_pk_mul_f32 v[70:71], v[70:71], v[88:89] op_sel_hi:[1,0]
	v_pk_mul_f32 v[72:73], v[72:73], v[88:89] op_sel_hi:[1,0]
	v_pk_mul_f32 v[74:75], v[74:75], v[88:89] op_sel_hi:[1,0]
	v_pk_mul_f32 v[76:77], v[76:77], v[88:89] op_sel_hi:[1,0]
	v_pk_mul_f32 v[78:79], v[78:79], v[88:89] op_sel_hi:[1,0]
	v_pk_mul_f32 v[48:49], v[48:49], v[88:89] op_sel_hi:[1,0]
	v_pk_mul_f32 v[50:51], v[50:51], v[88:89] op_sel_hi:[1,0]
	v_pk_mul_f32 v[52:53], v[52:53], v[88:89] op_sel_hi:[1,0]
	v_pk_mul_f32 v[54:55], v[54:55], v[88:89] op_sel_hi:[1,0]
	v_pk_mul_f32 v[56:57], v[56:57], v[88:89] op_sel_hi:[1,0]
	v_pk_mul_f32 v[58:59], v[58:59], v[88:89] op_sel_hi:[1,0]
	v_pk_mul_f32 v[60:61], v[60:61], v[88:89] op_sel_hi:[1,0]
	v_pk_mul_f32 v[62:63], v[62:63], v[88:89] op_sel_hi:[1,0]
	v_pk_mul_f32 v[32:33], v[32:33], v[88:89] op_sel_hi:[1,0]
	v_pk_mul_f32 v[34:35], v[34:35], v[88:89] op_sel_hi:[1,0]
	v_pk_mul_f32 v[36:37], v[36:37], v[88:89] op_sel_hi:[1,0]
	v_pk_mul_f32 v[38:39], v[38:39], v[88:89] op_sel_hi:[1,0]
	v_pk_mul_f32 v[40:41], v[40:41], v[88:89] op_sel_hi:[1,0]
	v_pk_mul_f32 v[42:43], v[42:43], v[88:89] op_sel_hi:[1,0]
	v_pk_mul_f32 v[44:45], v[44:45], v[88:89] op_sel_hi:[1,0]
	v_pk_mul_f32 v[46:47], v[46:47], v[88:89] op_sel_hi:[1,0]
	v_pk_mul_f32 v[16:17], v[16:17], v[88:89] op_sel_hi:[1,0]
	v_pk_mul_f32 v[18:19], v[18:19], v[88:89] op_sel_hi:[1,0]
	v_pk_mul_f32 v[20:21], v[20:21], v[88:89] op_sel_hi:[1,0]
	v_pk_mul_f32 v[22:23], v[22:23], v[88:89] op_sel_hi:[1,0]
	v_pk_mul_f32 v[24:25], v[24:25], v[88:89] op_sel_hi:[1,0]
	v_pk_mul_f32 v[26:27], v[26:27], v[88:89] op_sel_hi:[1,0]
	v_pk_mul_f32 v[28:29], v[28:29], v[88:89] op_sel_hi:[1,0]
	v_pk_mul_f32 v[30:31], v[30:31], v[88:89] op_sel_hi:[1,0]
.LdsaA_s1_noresc:
	ds_read_b64 v[80:81], v199 offset:34880
	ds_read_b64 v[82:83], v227 offset:34880
	ds_read_b64 v[84:85], v199 offset:39520
	ds_read_b64 v[86:87], v227 offset:39520
	ds_read_b64 v[88:89], v199 offset:44032
	ds_read_b64 v[90:91], v227 offset:44032
	ds_read_b64 v[92:93], v199 offset:48672
	ds_read_b64 v[94:95], v227 offset:48672
	s_waitcnt lgkmcnt(8)
	v_mfma_f32_32x32x16_f16 v[64:79], v[236:239], v[228:231], v[64:79]
	v_mfma_f32_32x32x16_f16 v[48:63], v[240:243], v[228:231], v[48:63]
	v_mfma_f32_32x32x16_f16 v[32:47], v[244:247], v[228:231], v[32:47]
	v_mfma_f32_32x32x16_f16 v[16:31], v[248:251], v[228:231], v[16:31]
	s_waitcnt lgkmcnt(0)
	v_mfma_f32_32x32x16_f16 v[64:79], v[80:83], v[232:235], v[64:79]
	v_mfma_f32_32x32x16_f16 v[48:63], v[84:87], v[232:235], v[48:63]
	v_mfma_f32_32x32x16_f16 v[32:47], v[88:91], v[232:235], v[32:47]
	v_mfma_f32_32x32x16_f16 v[16:31], v[92:95], v[232:235], v[16:31]
.LdsaA_s1_skip:
.LBB0_588:
	s_add_i32 s30, s30, 1
	s_add_i32 s31, s31, 64
	s_cmp_lg_u32 s34, s83
	v_subrev_u32_e32 v196, 64, v196
	s_waitcnt lgkmcnt(0)
	s_barrier
	s_cbranch_scc0 .LBB0_590
	s_waitcnt vmcnt(0)
	v_mov_b64_e32 v[150:151], v[148:149]
	s_branch .LBB0_512
